# P7 epilogue rewritten by hand: conv taps as v_fmac_f32_dpp with lane-masked fix-up weights, packed results in place, halo rows first
# speedup vs baseline: 1.0429x; 1.0201x over previous
.LBB0_1104:
	v_readlane_b32 s90, v240, 36
	v_readlane_b32 s91, v240, 37
	v_readlane_b32 s35, v240, 38
	v_readlane_b32 s45, v240, 39
	v_cmp_eq_u32_e64 s[52:53], 0, v154
	s_add_u32 s74, s90, 0x0
	s_addc_u32 s75, s91, 0
	s_add_u32 s76, s90, 0x5800
	s_addc_u32 s77, s91, 0
	s_add_u32 s78, s90, 0xb000
	s_addc_u32 s79, s91, 0
	s_add_u32 s80, s90, 0x2c00
	s_addc_u32 s81, s91, 0
	s_add_u32 s82, s90, 0x8400
	s_addc_u32 s83, s91, 0
	s_add_u32 s84, s90, 0xdc00
	s_addc_u32 s85, s91, 0
	s_add_u32 s86, s35, 0
	s_addc_u32 s87, s45, 0
	s_add_u32 s88, s35, 0x2c00
	s_addc_u32 s89, s45, 0
	s_add_u32 s48, s94, 0x6500000
	s_addc_u32 s49, s95, 0
	s_add_u32 s50, s94, 0x1d600000
	s_addc_u32 s51, s95, 0
	v_lshl_or_b32 v128, s46, 7, v191
	s_lshl_b32 s47, s44, 8
	v_add_u32_e32 v129, s47, v155
	v_mul_u32_u24_e32 v129, 0x1600, v129
	v_lshl_add_u32 v129, v128, 1, v129
	v_lshlrev_b32_e32 v128, 2, v128
	global_load_dwordx4 v[196:199], v128, s[74:75]
	global_load_dwordx4 v[200:203], v128, s[76:77]
	global_load_dwordx4 v[204:207], v128, s[78:79]
	global_load_dwordx4 v[208:211], v128, s[86:87]
	global_load_dwordx4 v[212:215], v128, s[80:81]
	global_load_dwordx4 v[216:219], v128, s[82:83]
	global_load_dwordx4 v[220:223], v128, s[84:85]
	global_load_dwordx4 v[224:227], v128, s[88:89]
	s_lshl_b32 s47, s44, 4
	s_lshl_b32 s90, s33, 2
	s_add_i32 s47, s47, s90
	v_lshl_or_b32 v132, s46, 8, v191
	v_add_u32_e32 v130, s47, v154
	v_add_u32_e32 v131, s47, v156
	v_mul_u32_u24_e32 v130, 0x2c00, v130
	v_mul_u32_u24_e32 v131, 0x2c00, v131
	v_lshl_add_u32 v130, v132, 1, v130
	v_lshl_add_u32 v131, v132, 1, v131
	s_mov_b64 exec, s[0:1]
	v_cvt_pk_bf16_f32 v120, v142, v143
	v_cvt_pk_bf16_f32 v121, v144, v145
	v_cvt_pk_bf16_f32 v122, v60, v61
	v_cvt_pk_bf16_f32 v123, v62, v63
	global_store_dwordx4 v130, v[120:123], s[50:51]
	v_cvt_pk_bf16_f32 v124, v108, v109
	v_cvt_pk_bf16_f32 v125, v110, v111
	v_cvt_pk_bf16_f32 v126, v56, v57
	v_cvt_pk_bf16_f32 v127, v58, v59
	global_store_dwordx4 v130, v[124:127], s[50:51] offset:256
	s_mov_b64 exec, s[6:7]
	v_cvt_pk_bf16_f32 v120, v100, v101
	v_cvt_pk_bf16_f32 v121, v102, v103
	v_cvt_pk_bf16_f32 v122, v36, v37
	v_cvt_pk_bf16_f32 v123, v38, v39
	global_store_dwordx4 v131, v[120:123], s[50:51]
	v_cvt_pk_bf16_f32 v124, v96, v97
	v_cvt_pk_bf16_f32 v125, v98, v99
	v_cvt_pk_bf16_f32 v126, v32, v33
	v_cvt_pk_bf16_f32 v127, v34, v35
	global_store_dwordx4 v131, v[124:127], s[50:51] offset:256
	s_mov_b64 exec, s[0:1]
	v_cvt_pk_bf16_f32 v120, v92, v93
	v_cvt_pk_bf16_f32 v121, v94, v95
	v_cvt_pk_bf16_f32 v122, v28, v29
	v_cvt_pk_bf16_f32 v123, v30, v31
	v_add_u32_e32 v132, 0x16000, v130
	global_store_dwordx4 v132, v[120:123], s[50:51]
	v_cvt_pk_bf16_f32 v124, v88, v89
	v_cvt_pk_bf16_f32 v125, v90, v91
	v_cvt_pk_bf16_f32 v126, v24, v25
	v_cvt_pk_bf16_f32 v127, v26, v27
	v_add_u32_e32 v132, 0x16100, v130
	global_store_dwordx4 v132, v[124:127], s[50:51]
	s_mov_b64 exec, s[6:7]
	v_cvt_pk_bf16_f32 v120, v68, v69
	v_cvt_pk_bf16_f32 v121, v70, v71
	v_cvt_pk_bf16_f32 v122, v4, v5
	v_cvt_pk_bf16_f32 v123, v6, v7
	v_add_u32_e32 v132, 0x16000, v131
	global_store_dwordx4 v132, v[120:123], s[50:51]
	v_cvt_pk_bf16_f32 v124, v64, v65
	v_cvt_pk_bf16_f32 v125, v66, v67
	v_cvt_pk_bf16_f32 v126, v0, v1
	v_cvt_pk_bf16_f32 v127, v2, v3
	v_add_u32_e32 v132, 0x16100, v131
	global_store_dwordx4 v132, v[124:127], s[50:51]
	s_mov_b64 exec, -1
	s_waitcnt vmcnt(8)
	v_cndmask_b32_e64 v166, 0, v200, s[52:53]
	v_cndmask_b32_e64 v170, 0, v196, s[0:1]
	v_cndmask_b32_e64 v174, 0, v216, s[52:53]
	v_cndmask_b32_e64 v178, 0, v212, s[0:1]
	v_cndmask_b32_e64 v167, 0, v201, s[52:53]
	v_cndmask_b32_e64 v171, 0, v197, s[0:1]
	v_cndmask_b32_e64 v175, 0, v217, s[52:53]
	v_cndmask_b32_e64 v179, 0, v213, s[0:1]
	v_cndmask_b32_e64 v168, 0, v202, s[52:53]
	v_cndmask_b32_e64 v172, 0, v198, s[0:1]
	v_cndmask_b32_e64 v176, 0, v218, s[52:53]
	v_cndmask_b32_e64 v180, 0, v214, s[0:1]
	v_cndmask_b32_e64 v169, 0, v203, s[52:53]
	v_cndmask_b32_e64 v173, 0, v199, s[0:1]
	v_cndmask_b32_e64 v177, 0, v219, s[52:53]
	v_cndmask_b32_e64 v181, 0, v215, s[0:1]
	v_fma_f32 v182, v204, v100, v208
	v_fma_f32 v183, v205, v101, v209
	v_fma_f32 v184, v206, v102, v210
	v_fma_f32 v185, v207, v103, v211
	v_fma_f32 v186, v220, v96, v224
	v_fma_f32 v187, v221, v97, v225
	v_fma_f32 v188, v222, v98, v226
	v_fma_f32 v189, v223, v99, v227
	v_fmac_f32_dpp v182, v100, v200 row_shr:1 row_mask:0xf bank_mask:0xf
	v_fmac_f32_dpp v183, v101, v201 row_shr:1 row_mask:0xf bank_mask:0xf
	v_fmac_f32_dpp v184, v102, v202 row_shr:1 row_mask:0xf bank_mask:0xf
	v_fmac_f32_dpp v185, v103, v203 row_shr:1 row_mask:0xf bank_mask:0xf
	v_fmac_f32_dpp v186, v96, v216 row_shr:1 row_mask:0xf bank_mask:0xf
	v_fmac_f32_dpp v187, v97, v217 row_shr:1 row_mask:0xf bank_mask:0xf
	v_fmac_f32_dpp v188, v98, v218 row_shr:1 row_mask:0xf bank_mask:0xf
	v_fmac_f32_dpp v189, v99, v219 row_shr:1 row_mask:0xf bank_mask:0xf
	v_fmac_f32_dpp v182, v100, v196 row_shr:2 row_mask:0xf bank_mask:0xf
	v_fmac_f32_dpp v183, v101, v197 row_shr:2 row_mask:0xf bank_mask:0xf
	v_fmac_f32_dpp v184, v102, v198 row_shr:2 row_mask:0xf bank_mask:0xf
	v_fmac_f32_dpp v185, v103, v199 row_shr:2 row_mask:0xf bank_mask:0xf
	v_fmac_f32_dpp v186, v96, v212 row_shr:2 row_mask:0xf bank_mask:0xf
	v_fmac_f32_dpp v187, v97, v213 row_shr:2 row_mask:0xf bank_mask:0xf
	v_fmac_f32_dpp v188, v98, v214 row_shr:2 row_mask:0xf bank_mask:0xf
	v_fmac_f32_dpp v189, v99, v215 row_shr:2 row_mask:0xf bank_mask:0xf
	v_fmac_f32_dpp v182, v112, v166 row_ror:1 row_mask:0xf bank_mask:0xf
	v_fmac_f32_dpp v183, v113, v167 row_ror:1 row_mask:0xf bank_mask:0xf
	v_fmac_f32_dpp v184, v114, v168 row_ror:1 row_mask:0xf bank_mask:0xf
	v_fmac_f32_dpp v185, v115, v169 row_ror:1 row_mask:0xf bank_mask:0xf
	v_fmac_f32_dpp v186, v104, v174 row_ror:1 row_mask:0xf bank_mask:0xf
	v_fmac_f32_dpp v187, v105, v175 row_ror:1 row_mask:0xf bank_mask:0xf
	v_fmac_f32_dpp v188, v106, v176 row_ror:1 row_mask:0xf bank_mask:0xf
	v_fmac_f32_dpp v189, v107, v177 row_ror:1 row_mask:0xf bank_mask:0xf
	v_fmac_f32_dpp v182, v112, v170 row_ror:2 row_mask:0xf bank_mask:0xf
	v_fmac_f32_dpp v183, v113, v171 row_ror:2 row_mask:0xf bank_mask:0xf
	v_fmac_f32_dpp v184, v114, v172 row_ror:2 row_mask:0xf bank_mask:0xf
	v_fmac_f32_dpp v185, v115, v173 row_ror:2 row_mask:0xf bank_mask:0xf
	v_fmac_f32_dpp v186, v104, v178 row_ror:2 row_mask:0xf bank_mask:0xf
	v_fmac_f32_dpp v187, v105, v179 row_ror:2 row_mask:0xf bank_mask:0xf
	v_fmac_f32_dpp v188, v106, v180 row_ror:2 row_mask:0xf bank_mask:0xf
	v_fmac_f32_dpp v189, v107, v181 row_ror:2 row_mask:0xf bank_mask:0xf
	v_mul_f32_e32 v116, 0xbfb8aa3b, v182
	v_mul_f32_e32 v117, 0xbfb8aa3b, v183
	v_mul_f32_e32 v118, 0xbfb8aa3b, v184
	v_mul_f32_e32 v119, 0xbfb8aa3b, v185
	v_exp_f32_e32 v116, v116
	v_exp_f32_e32 v117, v117
	v_exp_f32_e32 v118, v118
	v_exp_f32_e32 v119, v119
	v_add_f32_e32 v116, 1.0, v116
	v_add_f32_e32 v117, 1.0, v117
	v_add_f32_e32 v118, 1.0, v118
	v_add_f32_e32 v119, 1.0, v119
	v_rcp_f32_e32 v116, v116
	v_rcp_f32_e32 v117, v117
	v_rcp_f32_e32 v118, v118
	v_rcp_f32_e32 v119, v119
	v_mul_f32_e32 v116, v182, v116
	v_mul_f32_e32 v117, v183, v117
	v_mul_f32_e32 v118, v184, v118
	v_mul_f32_e32 v119, v185, v119
	v_mul_f32_e32 v116, v116, v186
	v_mul_f32_e32 v117, v117, v187
	v_mul_f32_e32 v118, v118, v188
	v_mul_f32_e32 v119, v119, v189
	v_cvt_pk_bf16_f32 v100, v116, v117
	v_cvt_pk_bf16_f32 v101, v118, v119
	v_fma_f32 v182, v204, v112, v208
	v_fma_f32 v183, v205, v113, v209
	v_fma_f32 v184, v206, v114, v210
	v_fma_f32 v185, v207, v115, v211
	v_fma_f32 v186, v220, v104, v224
	v_fma_f32 v187, v221, v105, v225
	v_fma_f32 v188, v222, v106, v226
	v_fma_f32 v189, v223, v107, v227
	v_fmac_f32_dpp v182, v112, v200 row_shr:1 row_mask:0xf bank_mask:0xf
	v_fmac_f32_dpp v183, v113, v201 row_shr:1 row_mask:0xf bank_mask:0xf
	v_fmac_f32_dpp v184, v114, v202 row_shr:1 row_mask:0xf bank_mask:0xf
	v_fmac_f32_dpp v185, v115, v203 row_shr:1 row_mask:0xf bank_mask:0xf
	v_fmac_f32_dpp v186, v104, v216 row_shr:1 row_mask:0xf bank_mask:0xf
	v_fmac_f32_dpp v187, v105, v217 row_shr:1 row_mask:0xf bank_mask:0xf
	v_fmac_f32_dpp v188, v106, v218 row_shr:1 row_mask:0xf bank_mask:0xf
	v_fmac_f32_dpp v189, v107, v219 row_shr:1 row_mask:0xf bank_mask:0xf
	v_fmac_f32_dpp v182, v112, v196 row_shr:2 row_mask:0xf bank_mask:0xf
	v_fmac_f32_dpp v183, v113, v197 row_shr:2 row_mask:0xf bank_mask:0xf
	v_fmac_f32_dpp v184, v114, v198 row_shr:2 row_mask:0xf bank_mask:0xf
	v_fmac_f32_dpp v185, v115, v199 row_shr:2 row_mask:0xf bank_mask:0xf
	v_fmac_f32_dpp v186, v104, v212 row_shr:2 row_mask:0xf bank_mask:0xf
	v_fmac_f32_dpp v187, v105, v213 row_shr:2 row_mask:0xf bank_mask:0xf
	v_fmac_f32_dpp v188, v106, v214 row_shr:2 row_mask:0xf bank_mask:0xf
	v_fmac_f32_dpp v189, v107, v215 row_shr:2 row_mask:0xf bank_mask:0xf
	v_fmac_f32_dpp v182, v138, v166 row_ror:1 row_mask:0xf bank_mask:0xf
	v_fmac_f32_dpp v183, v139, v167 row_ror:1 row_mask:0xf bank_mask:0xf
	v_fmac_f32_dpp v184, v140, v168 row_ror:1 row_mask:0xf bank_mask:0xf
	v_fmac_f32_dpp v185, v141, v169 row_ror:1 row_mask:0xf bank_mask:0xf
	v_fmac_f32_dpp v186, v134, v174 row_ror:1 row_mask:0xf bank_mask:0xf
	v_fmac_f32_dpp v187, v135, v175 row_ror:1 row_mask:0xf bank_mask:0xf
	v_fmac_f32_dpp v188, v136, v176 row_ror:1 row_mask:0xf bank_mask:0xf
	v_fmac_f32_dpp v189, v137, v177 row_ror:1 row_mask:0xf bank_mask:0xf
	v_fmac_f32_dpp v182, v138, v170 row_ror:2 row_mask:0xf bank_mask:0xf
	v_fmac_f32_dpp v183, v139, v171 row_ror:2 row_mask:0xf bank_mask:0xf
	v_fmac_f32_dpp v184, v140, v172 row_ror:2 row_mask:0xf bank_mask:0xf
	v_fmac_f32_dpp v185, v141, v173 row_ror:2 row_mask:0xf bank_mask:0xf
	v_fmac_f32_dpp v186, v134, v178 row_ror:2 row_mask:0xf bank_mask:0xf
	v_fmac_f32_dpp v187, v135, v179 row_ror:2 row_mask:0xf bank_mask:0xf
	v_fmac_f32_dpp v188, v136, v180 row_ror:2 row_mask:0xf bank_mask:0xf
	v_fmac_f32_dpp v189, v137, v181 row_ror:2 row_mask:0xf bank_mask:0xf
	v_mul_f32_e32 v116, 0xbfb8aa3b, v182
	v_mul_f32_e32 v117, 0xbfb8aa3b, v183
	v_mul_f32_e32 v118, 0xbfb8aa3b, v184
	v_mul_f32_e32 v119, 0xbfb8aa3b, v185
	v_exp_f32_e32 v116, v116
	v_exp_f32_e32 v117, v117
	v_exp_f32_e32 v118, v118
	v_exp_f32_e32 v119, v119
	v_add_f32_e32 v116, 1.0, v116
	v_add_f32_e32 v117, 1.0, v117
	v_add_f32_e32 v118, 1.0, v118
	v_add_f32_e32 v119, 1.0, v119
	v_rcp_f32_e32 v116, v116
	v_rcp_f32_e32 v117, v117
	v_rcp_f32_e32 v118, v118
	v_rcp_f32_e32 v119, v119
	v_mul_f32_e32 v116, v182, v116
	v_mul_f32_e32 v117, v183, v117
	v_mul_f32_e32 v118, v184, v118
	v_mul_f32_e32 v119, v185, v119
	v_mul_f32_e32 v116, v116, v186
	v_mul_f32_e32 v117, v117, v187
	v_mul_f32_e32 v118, v118, v188
	v_mul_f32_e32 v119, v119, v189
	v_cvt_pk_bf16_f32 v112, v116, v117
	v_cvt_pk_bf16_f32 v113, v118, v119
	v_fma_f32 v182, v204, v138, v208
	v_fma_f32 v183, v205, v139, v209
	v_fma_f32 v184, v206, v140, v210
	v_fma_f32 v185, v207, v141, v211
	v_fma_f32 v186, v220, v134, v224
	v_fma_f32 v187, v221, v135, v225
	v_fma_f32 v188, v222, v136, v226
	v_fma_f32 v189, v223, v137, v227
	v_fmac_f32_dpp v182, v138, v200 row_shr:1 row_mask:0xf bank_mask:0xf
	v_fmac_f32_dpp v183, v139, v201 row_shr:1 row_mask:0xf bank_mask:0xf
	v_fmac_f32_dpp v184, v140, v202 row_shr:1 row_mask:0xf bank_mask:0xf
	v_fmac_f32_dpp v185, v141, v203 row_shr:1 row_mask:0xf bank_mask:0xf
	v_fmac_f32_dpp v186, v134, v216 row_shr:1 row_mask:0xf bank_mask:0xf
	v_fmac_f32_dpp v187, v135, v217 row_shr:1 row_mask:0xf bank_mask:0xf
	v_fmac_f32_dpp v188, v136, v218 row_shr:1 row_mask:0xf bank_mask:0xf
	v_fmac_f32_dpp v189, v137, v219 row_shr:1 row_mask:0xf bank_mask:0xf
	v_fmac_f32_dpp v182, v138, v196 row_shr:2 row_mask:0xf bank_mask:0xf
	v_fmac_f32_dpp v183, v139, v197 row_shr:2 row_mask:0xf bank_mask:0xf
	v_fmac_f32_dpp v184, v140, v198 row_shr:2 row_mask:0xf bank_mask:0xf
	v_fmac_f32_dpp v185, v141, v199 row_shr:2 row_mask:0xf bank_mask:0xf
	v_fmac_f32_dpp v186, v134, v212 row_shr:2 row_mask:0xf bank_mask:0xf
	v_fmac_f32_dpp v187, v135, v213 row_shr:2 row_mask:0xf bank_mask:0xf
	v_fmac_f32_dpp v188, v136, v214 row_shr:2 row_mask:0xf bank_mask:0xf
	v_fmac_f32_dpp v189, v137, v215 row_shr:2 row_mask:0xf bank_mask:0xf
	v_fmac_f32_dpp v182, v142, v166 row_ror:1 row_mask:0xf bank_mask:0xf
	v_fmac_f32_dpp v183, v143, v167 row_ror:1 row_mask:0xf bank_mask:0xf
	v_fmac_f32_dpp v184, v144, v168 row_ror:1 row_mask:0xf bank_mask:0xf
	v_fmac_f32_dpp v185, v145, v169 row_ror:1 row_mask:0xf bank_mask:0xf
	v_fmac_f32_dpp v186, v108, v174 row_ror:1 row_mask:0xf bank_mask:0xf
	v_fmac_f32_dpp v187, v109, v175 row_ror:1 row_mask:0xf bank_mask:0xf
	v_fmac_f32_dpp v188, v110, v176 row_ror:1 row_mask:0xf bank_mask:0xf
	v_fmac_f32_dpp v189, v111, v177 row_ror:1 row_mask:0xf bank_mask:0xf
	v_fmac_f32_dpp v182, v142, v170 row_ror:2 row_mask:0xf bank_mask:0xf
	v_fmac_f32_dpp v183, v143, v171 row_ror:2 row_mask:0xf bank_mask:0xf
	v_fmac_f32_dpp v184, v144, v172 row_ror:2 row_mask:0xf bank_mask:0xf
	v_fmac_f32_dpp v185, v145, v173 row_ror:2 row_mask:0xf bank_mask:0xf
	v_fmac_f32_dpp v186, v108, v178 row_ror:2 row_mask:0xf bank_mask:0xf
	v_fmac_f32_dpp v187, v109, v179 row_ror:2 row_mask:0xf bank_mask:0xf
	v_fmac_f32_dpp v188, v110, v180 row_ror:2 row_mask:0xf bank_mask:0xf
	v_fmac_f32_dpp v189, v111, v181 row_ror:2 row_mask:0xf bank_mask:0xf
	v_mul_f32_e32 v116, 0xbfb8aa3b, v182
	v_mul_f32_e32 v117, 0xbfb8aa3b, v183
	v_mul_f32_e32 v118, 0xbfb8aa3b, v184
	v_mul_f32_e32 v119, 0xbfb8aa3b, v185
	v_exp_f32_e32 v116, v116
	v_exp_f32_e32 v117, v117
	v_exp_f32_e32 v118, v118
	v_exp_f32_e32 v119, v119
	v_add_f32_e32 v116, 1.0, v116
	v_add_f32_e32 v117, 1.0, v117
	v_add_f32_e32 v118, 1.0, v118
	v_add_f32_e32 v119, 1.0, v119
	v_rcp_f32_e32 v116, v116
	v_rcp_f32_e32 v117, v117
	v_rcp_f32_e32 v118, v118
	v_rcp_f32_e32 v119, v119
	v_mul_f32_e32 v116, v182, v116
	v_mul_f32_e32 v117, v183, v117
	v_mul_f32_e32 v118, v184, v118
	v_mul_f32_e32 v119, v185, v119
	v_mul_f32_e32 v116, v116, v186
	v_mul_f32_e32 v117, v117, v187
	v_mul_f32_e32 v118, v118, v188
	v_mul_f32_e32 v119, v119, v189
	v_cvt_pk_bf16_f32 v138, v116, v117
	v_cvt_pk_bf16_f32 v139, v118, v119
	v_fma_f32 v182, v204, v142, v208
	v_fma_f32 v183, v205, v143, v209
	v_fma_f32 v184, v206, v144, v210
	v_fma_f32 v185, v207, v145, v211
	v_fma_f32 v186, v220, v108, v224
	v_fma_f32 v187, v221, v109, v225
	v_fma_f32 v188, v222, v110, v226
	v_fma_f32 v189, v223, v111, v227
	v_fmac_f32_dpp v182, v142, v200 row_shr:1 row_mask:0xf bank_mask:0xf
	v_fmac_f32_dpp v183, v143, v201 row_shr:1 row_mask:0xf bank_mask:0xf
	v_fmac_f32_dpp v184, v144, v202 row_shr:1 row_mask:0xf bank_mask:0xf
	v_fmac_f32_dpp v185, v145, v203 row_shr:1 row_mask:0xf bank_mask:0xf
	v_fmac_f32_dpp v186, v108, v216 row_shr:1 row_mask:0xf bank_mask:0xf
	v_fmac_f32_dpp v187, v109, v217 row_shr:1 row_mask:0xf bank_mask:0xf
	v_fmac_f32_dpp v188, v110, v218 row_shr:1 row_mask:0xf bank_mask:0xf
	v_fmac_f32_dpp v189, v111, v219 row_shr:1 row_mask:0xf bank_mask:0xf
	v_fmac_f32_dpp v182, v142, v196 row_shr:2 row_mask:0xf bank_mask:0xf
	v_fmac_f32_dpp v183, v143, v197 row_shr:2 row_mask:0xf bank_mask:0xf
	v_fmac_f32_dpp v184, v144, v198 row_shr:2 row_mask:0xf bank_mask:0xf
	v_fmac_f32_dpp v185, v145, v199 row_shr:2 row_mask:0xf bank_mask:0xf
	v_fmac_f32_dpp v186, v108, v212 row_shr:2 row_mask:0xf bank_mask:0xf
	v_fmac_f32_dpp v187, v109, v213 row_shr:2 row_mask:0xf bank_mask:0xf
	v_fmac_f32_dpp v188, v110, v214 row_shr:2 row_mask:0xf bank_mask:0xf
	v_fmac_f32_dpp v189, v111, v215 row_shr:2 row_mask:0xf bank_mask:0xf
	v_mul_f32_e32 v116, 0xbfb8aa3b, v182
	v_mul_f32_e32 v117, 0xbfb8aa3b, v183
	v_mul_f32_e32 v118, 0xbfb8aa3b, v184
	v_mul_f32_e32 v119, 0xbfb8aa3b, v185
	v_exp_f32_e32 v116, v116
	v_exp_f32_e32 v117, v117
	v_exp_f32_e32 v118, v118
	v_exp_f32_e32 v119, v119
	v_add_f32_e32 v116, 1.0, v116
	v_add_f32_e32 v117, 1.0, v117
	v_add_f32_e32 v118, 1.0, v118
	v_add_f32_e32 v119, 1.0, v119
	v_rcp_f32_e32 v116, v116
	v_rcp_f32_e32 v117, v117
	v_rcp_f32_e32 v118, v118
	v_rcp_f32_e32 v119, v119
	v_mul_f32_e32 v116, v182, v116
	v_mul_f32_e32 v117, v183, v117
	v_mul_f32_e32 v118, v184, v118
	v_mul_f32_e32 v119, v185, v119
	v_mul_f32_e32 v116, v116, v186
	v_mul_f32_e32 v117, v117, v187
	v_mul_f32_e32 v118, v118, v188
	v_mul_f32_e32 v119, v119, v189
	v_cvt_pk_bf16_f32 v142, v116, v117
	v_cvt_pk_bf16_f32 v143, v118, v119
	v_fma_f32 v182, v204, v68, v208
	v_fma_f32 v183, v205, v69, v209
	v_fma_f32 v184, v206, v70, v210
	v_fma_f32 v185, v207, v71, v211
	v_fma_f32 v186, v220, v64, v224
	v_fma_f32 v187, v221, v65, v225
	v_fma_f32 v188, v222, v66, v226
	v_fma_f32 v189, v223, v67, v227
	v_fmac_f32_dpp v182, v68, v200 row_shr:1 row_mask:0xf bank_mask:0xf
	v_fmac_f32_dpp v183, v69, v201 row_shr:1 row_mask:0xf bank_mask:0xf
	v_fmac_f32_dpp v184, v70, v202 row_shr:1 row_mask:0xf bank_mask:0xf
	v_fmac_f32_dpp v185, v71, v203 row_shr:1 row_mask:0xf bank_mask:0xf
	v_fmac_f32_dpp v186, v64, v216 row_shr:1 row_mask:0xf bank_mask:0xf
	v_fmac_f32_dpp v187, v65, v217 row_shr:1 row_mask:0xf bank_mask:0xf
	v_fmac_f32_dpp v188, v66, v218 row_shr:1 row_mask:0xf bank_mask:0xf
	v_fmac_f32_dpp v189, v67, v219 row_shr:1 row_mask:0xf bank_mask:0xf
	v_fmac_f32_dpp v182, v68, v196 row_shr:2 row_mask:0xf bank_mask:0xf
	v_fmac_f32_dpp v183, v69, v197 row_shr:2 row_mask:0xf bank_mask:0xf
	v_fmac_f32_dpp v184, v70, v198 row_shr:2 row_mask:0xf bank_mask:0xf
	v_fmac_f32_dpp v185, v71, v199 row_shr:2 row_mask:0xf bank_mask:0xf
	v_fmac_f32_dpp v186, v64, v212 row_shr:2 row_mask:0xf bank_mask:0xf
	v_fmac_f32_dpp v187, v65, v213 row_shr:2 row_mask:0xf bank_mask:0xf
	v_fmac_f32_dpp v188, v66, v214 row_shr:2 row_mask:0xf bank_mask:0xf
	v_fmac_f32_dpp v189, v67, v215 row_shr:2 row_mask:0xf bank_mask:0xf
	v_fmac_f32_dpp v182, v76, v166 row_ror:1 row_mask:0xf bank_mask:0xf
	v_fmac_f32_dpp v183, v77, v167 row_ror:1 row_mask:0xf bank_mask:0xf
	v_fmac_f32_dpp v184, v78, v168 row_ror:1 row_mask:0xf bank_mask:0xf
	v_fmac_f32_dpp v185, v79, v169 row_ror:1 row_mask:0xf bank_mask:0xf
	v_fmac_f32_dpp v186, v72, v174 row_ror:1 row_mask:0xf bank_mask:0xf
	v_fmac_f32_dpp v187, v73, v175 row_ror:1 row_mask:0xf bank_mask:0xf
	v_fmac_f32_dpp v188, v74, v176 row_ror:1 row_mask:0xf bank_mask:0xf
	v_fmac_f32_dpp v189, v75, v177 row_ror:1 row_mask:0xf bank_mask:0xf
	v_fmac_f32_dpp v182, v76, v170 row_ror:2 row_mask:0xf bank_mask:0xf
	v_fmac_f32_dpp v183, v77, v171 row_ror:2 row_mask:0xf bank_mask:0xf
	v_fmac_f32_dpp v184, v78, v172 row_ror:2 row_mask:0xf bank_mask:0xf
	v_fmac_f32_dpp v185, v79, v173 row_ror:2 row_mask:0xf bank_mask:0xf
	v_fmac_f32_dpp v186, v72, v178 row_ror:2 row_mask:0xf bank_mask:0xf
	v_fmac_f32_dpp v187, v73, v179 row_ror:2 row_mask:0xf bank_mask:0xf
	v_fmac_f32_dpp v188, v74, v180 row_ror:2 row_mask:0xf bank_mask:0xf
	v_fmac_f32_dpp v189, v75, v181 row_ror:2 row_mask:0xf bank_mask:0xf
	v_mul_f32_e32 v116, 0xbfb8aa3b, v182
	v_mul_f32_e32 v117, 0xbfb8aa3b, v183
	v_mul_f32_e32 v118, 0xbfb8aa3b, v184
	v_mul_f32_e32 v119, 0xbfb8aa3b, v185
	v_exp_f32_e32 v116, v116
	v_exp_f32_e32 v117, v117
	v_exp_f32_e32 v118, v118
	v_exp_f32_e32 v119, v119
	v_add_f32_e32 v116, 1.0, v116
	v_add_f32_e32 v117, 1.0, v117
	v_add_f32_e32 v118, 1.0, v118
	v_add_f32_e32 v119, 1.0, v119
	v_rcp_f32_e32 v116, v116
	v_rcp_f32_e32 v117, v117
	v_rcp_f32_e32 v118, v118
	v_rcp_f32_e32 v119, v119
	v_mul_f32_e32 v116, v182, v116
	v_mul_f32_e32 v117, v183, v117
	v_mul_f32_e32 v118, v184, v118
	v_mul_f32_e32 v119, v185, v119
	v_mul_f32_e32 v116, v116, v186
	v_mul_f32_e32 v117, v117, v187
	v_mul_f32_e32 v118, v118, v188
	v_mul_f32_e32 v119, v119, v189
	v_cvt_pk_bf16_f32 v68, v116, v117
	v_cvt_pk_bf16_f32 v69, v118, v119
	v_fma_f32 v182, v204, v76, v208
	v_fma_f32 v183, v205, v77, v209
	v_fma_f32 v184, v206, v78, v210
	v_fma_f32 v185, v207, v79, v211
	v_fma_f32 v186, v220, v72, v224
	v_fma_f32 v187, v221, v73, v225
	v_fma_f32 v188, v222, v74, v226
	v_fma_f32 v189, v223, v75, v227
	v_fmac_f32_dpp v182, v76, v200 row_shr:1 row_mask:0xf bank_mask:0xf
	v_fmac_f32_dpp v183, v77, v201 row_shr:1 row_mask:0xf bank_mask:0xf
	v_fmac_f32_dpp v184, v78, v202 row_shr:1 row_mask:0xf bank_mask:0xf
	v_fmac_f32_dpp v185, v79, v203 row_shr:1 row_mask:0xf bank_mask:0xf
	v_fmac_f32_dpp v186, v72, v216 row_shr:1 row_mask:0xf bank_mask:0xf
	v_fmac_f32_dpp v187, v73, v217 row_shr:1 row_mask:0xf bank_mask:0xf
	v_fmac_f32_dpp v188, v74, v218 row_shr:1 row_mask:0xf bank_mask:0xf
	v_fmac_f32_dpp v189, v75, v219 row_shr:1 row_mask:0xf bank_mask:0xf
	v_fmac_f32_dpp v182, v76, v196 row_shr:2 row_mask:0xf bank_mask:0xf
	v_fmac_f32_dpp v183, v77, v197 row_shr:2 row_mask:0xf bank_mask:0xf
	v_fmac_f32_dpp v184, v78, v198 row_shr:2 row_mask:0xf bank_mask:0xf
	v_fmac_f32_dpp v185, v79, v199 row_shr:2 row_mask:0xf bank_mask:0xf
	v_fmac_f32_dpp v186, v72, v212 row_shr:2 row_mask:0xf bank_mask:0xf
	v_fmac_f32_dpp v187, v73, v213 row_shr:2 row_mask:0xf bank_mask:0xf
	v_fmac_f32_dpp v188, v74, v214 row_shr:2 row_mask:0xf bank_mask:0xf
	v_fmac_f32_dpp v189, v75, v215 row_shr:2 row_mask:0xf bank_mask:0xf
	v_fmac_f32_dpp v182, v84, v166 row_ror:1 row_mask:0xf bank_mask:0xf
	v_fmac_f32_dpp v183, v85, v167 row_ror:1 row_mask:0xf bank_mask:0xf
	v_fmac_f32_dpp v184, v86, v168 row_ror:1 row_mask:0xf bank_mask:0xf
	v_fmac_f32_dpp v185, v87, v169 row_ror:1 row_mask:0xf bank_mask:0xf
	v_fmac_f32_dpp v186, v80, v174 row_ror:1 row_mask:0xf bank_mask:0xf
	v_fmac_f32_dpp v187, v81, v175 row_ror:1 row_mask:0xf bank_mask:0xf
	v_fmac_f32_dpp v188, v82, v176 row_ror:1 row_mask:0xf bank_mask:0xf
	v_fmac_f32_dpp v189, v83, v177 row_ror:1 row_mask:0xf bank_mask:0xf
	v_fmac_f32_dpp v182, v84, v170 row_ror:2 row_mask:0xf bank_mask:0xf
	v_fmac_f32_dpp v183, v85, v171 row_ror:2 row_mask:0xf bank_mask:0xf
	v_fmac_f32_dpp v184, v86, v172 row_ror:2 row_mask:0xf bank_mask:0xf
	v_fmac_f32_dpp v185, v87, v173 row_ror:2 row_mask:0xf bank_mask:0xf
	v_fmac_f32_dpp v186, v80, v178 row_ror:2 row_mask:0xf bank_mask:0xf
	v_fmac_f32_dpp v187, v81, v179 row_ror:2 row_mask:0xf bank_mask:0xf
	v_fmac_f32_dpp v188, v82, v180 row_ror:2 row_mask:0xf bank_mask:0xf
	v_fmac_f32_dpp v189, v83, v181 row_ror:2 row_mask:0xf bank_mask:0xf
	v_mul_f32_e32 v116, 0xbfb8aa3b, v182
	v_mul_f32_e32 v117, 0xbfb8aa3b, v183
	v_mul_f32_e32 v118, 0xbfb8aa3b, v184
	v_mul_f32_e32 v119, 0xbfb8aa3b, v185
	v_exp_f32_e32 v116, v116
	v_exp_f32_e32 v117, v117
	v_exp_f32_e32 v118, v118
	v_exp_f32_e32 v119, v119
	v_add_f32_e32 v116, 1.0, v116
	v_add_f32_e32 v117, 1.0, v117
	v_add_f32_e32 v118, 1.0, v118
	v_add_f32_e32 v119, 1.0, v119
	v_rcp_f32_e32 v116, v116
	v_rcp_f32_e32 v117, v117
	v_rcp_f32_e32 v118, v118
	v_rcp_f32_e32 v119, v119
	v_mul_f32_e32 v116, v182, v116
	v_mul_f32_e32 v117, v183, v117
	v_mul_f32_e32 v118, v184, v118
	v_mul_f32_e32 v119, v185, v119
	v_mul_f32_e32 v116, v116, v186
	v_mul_f32_e32 v117, v117, v187
	v_mul_f32_e32 v118, v118, v188
	v_mul_f32_e32 v119, v119, v189
	v_cvt_pk_bf16_f32 v76, v116, v117
	v_cvt_pk_bf16_f32 v77, v118, v119
	v_fma_f32 v182, v204, v84, v208
	v_fma_f32 v183, v205, v85, v209
	v_fma_f32 v184, v206, v86, v210
	v_fma_f32 v185, v207, v87, v211
	v_fma_f32 v186, v220, v80, v224
	v_fma_f32 v187, v221, v81, v225
	v_fma_f32 v188, v222, v82, v226
	v_fma_f32 v189, v223, v83, v227
	v_fmac_f32_dpp v182, v84, v200 row_shr:1 row_mask:0xf bank_mask:0xf
	v_fmac_f32_dpp v183, v85, v201 row_shr:1 row_mask:0xf bank_mask:0xf
	v_fmac_f32_dpp v184, v86, v202 row_shr:1 row_mask:0xf bank_mask:0xf
	v_fmac_f32_dpp v185, v87, v203 row_shr:1 row_mask:0xf bank_mask:0xf
	v_fmac_f32_dpp v186, v80, v216 row_shr:1 row_mask:0xf bank_mask:0xf
	v_fmac_f32_dpp v187, v81, v217 row_shr:1 row_mask:0xf bank_mask:0xf
	v_fmac_f32_dpp v188, v82, v218 row_shr:1 row_mask:0xf bank_mask:0xf
	v_fmac_f32_dpp v189, v83, v219 row_shr:1 row_mask:0xf bank_mask:0xf
	v_fmac_f32_dpp v182, v84, v196 row_shr:2 row_mask:0xf bank_mask:0xf
	v_fmac_f32_dpp v183, v85, v197 row_shr:2 row_mask:0xf bank_mask:0xf
	v_fmac_f32_dpp v184, v86, v198 row_shr:2 row_mask:0xf bank_mask:0xf
	v_fmac_f32_dpp v185, v87, v199 row_shr:2 row_mask:0xf bank_mask:0xf
	v_fmac_f32_dpp v186, v80, v212 row_shr:2 row_mask:0xf bank_mask:0xf
	v_fmac_f32_dpp v187, v81, v213 row_shr:2 row_mask:0xf bank_mask:0xf
	v_fmac_f32_dpp v188, v82, v214 row_shr:2 row_mask:0xf bank_mask:0xf
	v_fmac_f32_dpp v189, v83, v215 row_shr:2 row_mask:0xf bank_mask:0xf
	v_fmac_f32_dpp v182, v92, v166 row_ror:1 row_mask:0xf bank_mask:0xf
	v_fmac_f32_dpp v183, v93, v167 row_ror:1 row_mask:0xf bank_mask:0xf
	v_fmac_f32_dpp v184, v94, v168 row_ror:1 row_mask:0xf bank_mask:0xf
	v_fmac_f32_dpp v185, v95, v169 row_ror:1 row_mask:0xf bank_mask:0xf
	v_fmac_f32_dpp v186, v88, v174 row_ror:1 row_mask:0xf bank_mask:0xf
	v_fmac_f32_dpp v187, v89, v175 row_ror:1 row_mask:0xf bank_mask:0xf
	v_fmac_f32_dpp v188, v90, v176 row_ror:1 row_mask:0xf bank_mask:0xf
	v_fmac_f32_dpp v189, v91, v177 row_ror:1 row_mask:0xf bank_mask:0xf
	v_fmac_f32_dpp v182, v92, v170 row_ror:2 row_mask:0xf bank_mask:0xf
	v_fmac_f32_dpp v183, v93, v171 row_ror:2 row_mask:0xf bank_mask:0xf
	v_fmac_f32_dpp v184, v94, v172 row_ror:2 row_mask:0xf bank_mask:0xf
	v_fmac_f32_dpp v185, v95, v173 row_ror:2 row_mask:0xf bank_mask:0xf
	v_fmac_f32_dpp v186, v88, v178 row_ror:2 row_mask:0xf bank_mask:0xf
	v_fmac_f32_dpp v187, v89, v179 row_ror:2 row_mask:0xf bank_mask:0xf
	v_fmac_f32_dpp v188, v90, v180 row_ror:2 row_mask:0xf bank_mask:0xf
	v_fmac_f32_dpp v189, v91, v181 row_ror:2 row_mask:0xf bank_mask:0xf
	v_mul_f32_e32 v116, 0xbfb8aa3b, v182
	v_mul_f32_e32 v117, 0xbfb8aa3b, v183
	v_mul_f32_e32 v118, 0xbfb8aa3b, v184
	v_mul_f32_e32 v119, 0xbfb8aa3b, v185
	v_exp_f32_e32 v116, v116
	v_exp_f32_e32 v117, v117
	v_exp_f32_e32 v118, v118
	v_exp_f32_e32 v119, v119
	v_add_f32_e32 v116, 1.0, v116
	v_add_f32_e32 v117, 1.0, v117
	v_add_f32_e32 v118, 1.0, v118
	v_add_f32_e32 v119, 1.0, v119
	v_rcp_f32_e32 v116, v116
	v_rcp_f32_e32 v117, v117
	v_rcp_f32_e32 v118, v118
	v_rcp_f32_e32 v119, v119
	v_mul_f32_e32 v116, v182, v116
	v_mul_f32_e32 v117, v183, v117
	v_mul_f32_e32 v118, v184, v118
	v_mul_f32_e32 v119, v185, v119
	v_mul_f32_e32 v116, v116, v186
	v_mul_f32_e32 v117, v117, v187
	v_mul_f32_e32 v118, v118, v188
	v_mul_f32_e32 v119, v119, v189
	v_cvt_pk_bf16_f32 v84, v116, v117
	v_cvt_pk_bf16_f32 v85, v118, v119
	v_fma_f32 v182, v204, v92, v208
	v_fma_f32 v183, v205, v93, v209
	v_fma_f32 v184, v206, v94, v210
	v_fma_f32 v185, v207, v95, v211
	v_fma_f32 v186, v220, v88, v224
	v_fma_f32 v187, v221, v89, v225
	v_fma_f32 v188, v222, v90, v226
	v_fma_f32 v189, v223, v91, v227
	v_fmac_f32_dpp v182, v92, v200 row_shr:1 row_mask:0xf bank_mask:0xf
	v_fmac_f32_dpp v183, v93, v201 row_shr:1 row_mask:0xf bank_mask:0xf
	v_fmac_f32_dpp v184, v94, v202 row_shr:1 row_mask:0xf bank_mask:0xf
	v_fmac_f32_dpp v185, v95, v203 row_shr:1 row_mask:0xf bank_mask:0xf
	v_fmac_f32_dpp v186, v88, v216 row_shr:1 row_mask:0xf bank_mask:0xf
	v_fmac_f32_dpp v187, v89, v217 row_shr:1 row_mask:0xf bank_mask:0xf
	v_fmac_f32_dpp v188, v90, v218 row_shr:1 row_mask:0xf bank_mask:0xf
	v_fmac_f32_dpp v189, v91, v219 row_shr:1 row_mask:0xf bank_mask:0xf
	v_fmac_f32_dpp v182, v92, v196 row_shr:2 row_mask:0xf bank_mask:0xf
	v_fmac_f32_dpp v183, v93, v197 row_shr:2 row_mask:0xf bank_mask:0xf
	v_fmac_f32_dpp v184, v94, v198 row_shr:2 row_mask:0xf bank_mask:0xf
	v_fmac_f32_dpp v185, v95, v199 row_shr:2 row_mask:0xf bank_mask:0xf
	v_fmac_f32_dpp v186, v88, v212 row_shr:2 row_mask:0xf bank_mask:0xf
	v_fmac_f32_dpp v187, v89, v213 row_shr:2 row_mask:0xf bank_mask:0xf
	v_fmac_f32_dpp v188, v90, v214 row_shr:2 row_mask:0xf bank_mask:0xf
	v_fmac_f32_dpp v189, v91, v215 row_shr:2 row_mask:0xf bank_mask:0xf
	global_load_dwordx4 v[196:199], v128, s[74:75] offset:16
	global_load_dwordx4 v[200:203], v128, s[76:77] offset:16
	global_load_dwordx4 v[204:207], v128, s[78:79] offset:16
	global_load_dwordx4 v[208:211], v128, s[86:87] offset:16
	global_load_dwordx4 v[212:215], v128, s[80:81] offset:16
	global_load_dwordx4 v[216:219], v128, s[82:83] offset:16
	global_load_dwordx4 v[220:223], v128, s[84:85] offset:16
	global_load_dwordx4 v[224:227], v128, s[88:89] offset:16
	v_mul_f32_e32 v116, 0xbfb8aa3b, v182
	v_mul_f32_e32 v117, 0xbfb8aa3b, v183
	v_mul_f32_e32 v118, 0xbfb8aa3b, v184
	v_mul_f32_e32 v119, 0xbfb8aa3b, v185
	v_exp_f32_e32 v116, v116
	v_exp_f32_e32 v117, v117
	v_exp_f32_e32 v118, v118
	v_exp_f32_e32 v119, v119
	v_add_f32_e32 v116, 1.0, v116
	v_add_f32_e32 v117, 1.0, v117
	v_add_f32_e32 v118, 1.0, v118
	v_add_f32_e32 v119, 1.0, v119
	v_rcp_f32_e32 v116, v116
	v_rcp_f32_e32 v117, v117
	v_rcp_f32_e32 v118, v118
	v_rcp_f32_e32 v119, v119
	v_mul_f32_e32 v116, v182, v116
	v_mul_f32_e32 v117, v183, v117
	v_mul_f32_e32 v118, v184, v118
	v_mul_f32_e32 v119, v185, v119
	v_mul_f32_e32 v116, v116, v186
	v_mul_f32_e32 v117, v117, v187
	v_mul_f32_e32 v118, v118, v188
	v_mul_f32_e32 v119, v119, v189
	v_cvt_pk_bf16_f32 v92, v116, v117
	v_cvt_pk_bf16_f32 v93, v118, v119
	s_waitcnt vmcnt(0)
	v_cndmask_b32_e64 v166, 0, v200, s[52:53]
	v_cndmask_b32_e64 v170, 0, v196, s[0:1]
	v_cndmask_b32_e64 v174, 0, v216, s[52:53]
	v_cndmask_b32_e64 v178, 0, v212, s[0:1]
	v_cndmask_b32_e64 v167, 0, v201, s[52:53]
	v_cndmask_b32_e64 v171, 0, v197, s[0:1]
	v_cndmask_b32_e64 v175, 0, v217, s[52:53]
	v_cndmask_b32_e64 v179, 0, v213, s[0:1]
	v_cndmask_b32_e64 v168, 0, v202, s[52:53]
	v_cndmask_b32_e64 v172, 0, v198, s[0:1]
	v_cndmask_b32_e64 v176, 0, v218, s[52:53]
	v_cndmask_b32_e64 v180, 0, v214, s[0:1]
	v_cndmask_b32_e64 v169, 0, v203, s[52:53]
	v_cndmask_b32_e64 v173, 0, v199, s[0:1]
	v_cndmask_b32_e64 v177, 0, v219, s[52:53]
	v_cndmask_b32_e64 v181, 0, v215, s[0:1]
	v_fma_f32 v182, v204, v36, v208
	v_fma_f32 v183, v205, v37, v209
	v_fma_f32 v184, v206, v38, v210
	v_fma_f32 v185, v207, v39, v211
	v_fma_f32 v186, v220, v32, v224
	v_fma_f32 v187, v221, v33, v225
	v_fma_f32 v188, v222, v34, v226
	v_fma_f32 v189, v223, v35, v227
	v_fmac_f32_dpp v182, v36, v200 row_shr:1 row_mask:0xf bank_mask:0xf
	v_fmac_f32_dpp v183, v37, v201 row_shr:1 row_mask:0xf bank_mask:0xf
	v_fmac_f32_dpp v184, v38, v202 row_shr:1 row_mask:0xf bank_mask:0xf
	v_fmac_f32_dpp v185, v39, v203 row_shr:1 row_mask:0xf bank_mask:0xf
	v_fmac_f32_dpp v186, v32, v216 row_shr:1 row_mask:0xf bank_mask:0xf
	v_fmac_f32_dpp v187, v33, v217 row_shr:1 row_mask:0xf bank_mask:0xf
	v_fmac_f32_dpp v188, v34, v218 row_shr:1 row_mask:0xf bank_mask:0xf
	v_fmac_f32_dpp v189, v35, v219 row_shr:1 row_mask:0xf bank_mask:0xf
	v_fmac_f32_dpp v182, v36, v196 row_shr:2 row_mask:0xf bank_mask:0xf
	v_fmac_f32_dpp v183, v37, v197 row_shr:2 row_mask:0xf bank_mask:0xf
	v_fmac_f32_dpp v184, v38, v198 row_shr:2 row_mask:0xf bank_mask:0xf
	v_fmac_f32_dpp v185, v39, v199 row_shr:2 row_mask:0xf bank_mask:0xf
	v_fmac_f32_dpp v186, v32, v212 row_shr:2 row_mask:0xf bank_mask:0xf
	v_fmac_f32_dpp v187, v33, v213 row_shr:2 row_mask:0xf bank_mask:0xf
	v_fmac_f32_dpp v188, v34, v214 row_shr:2 row_mask:0xf bank_mask:0xf
	v_fmac_f32_dpp v189, v35, v215 row_shr:2 row_mask:0xf bank_mask:0xf
	v_fmac_f32_dpp v182, v44, v166 row_ror:1 row_mask:0xf bank_mask:0xf
	v_fmac_f32_dpp v183, v45, v167 row_ror:1 row_mask:0xf bank_mask:0xf
	v_fmac_f32_dpp v184, v46, v168 row_ror:1 row_mask:0xf bank_mask:0xf
	v_fmac_f32_dpp v185, v47, v169 row_ror:1 row_mask:0xf bank_mask:0xf
	v_fmac_f32_dpp v186, v40, v174 row_ror:1 row_mask:0xf bank_mask:0xf
	v_fmac_f32_dpp v187, v41, v175 row_ror:1 row_mask:0xf bank_mask:0xf
	v_fmac_f32_dpp v188, v42, v176 row_ror:1 row_mask:0xf bank_mask:0xf
	v_fmac_f32_dpp v189, v43, v177 row_ror:1 row_mask:0xf bank_mask:0xf
	v_fmac_f32_dpp v182, v44, v170 row_ror:2 row_mask:0xf bank_mask:0xf
	v_fmac_f32_dpp v183, v45, v171 row_ror:2 row_mask:0xf bank_mask:0xf
	v_fmac_f32_dpp v184, v46, v172 row_ror:2 row_mask:0xf bank_mask:0xf
	v_fmac_f32_dpp v185, v47, v173 row_ror:2 row_mask:0xf bank_mask:0xf
	v_fmac_f32_dpp v186, v40, v178 row_ror:2 row_mask:0xf bank_mask:0xf
	v_fmac_f32_dpp v187, v41, v179 row_ror:2 row_mask:0xf bank_mask:0xf
	v_fmac_f32_dpp v188, v42, v180 row_ror:2 row_mask:0xf bank_mask:0xf
	v_fmac_f32_dpp v189, v43, v181 row_ror:2 row_mask:0xf bank_mask:0xf
	v_mul_f32_e32 v116, 0xbfb8aa3b, v182
	v_mul_f32_e32 v117, 0xbfb8aa3b, v183
	v_mul_f32_e32 v118, 0xbfb8aa3b, v184
	v_mul_f32_e32 v119, 0xbfb8aa3b, v185
	v_exp_f32_e32 v116, v116
	v_exp_f32_e32 v117, v117
	v_exp_f32_e32 v118, v118
	v_exp_f32_e32 v119, v119
	v_add_f32_e32 v116, 1.0, v116
	v_add_f32_e32 v117, 1.0, v117
	v_add_f32_e32 v118, 1.0, v118
	v_add_f32_e32 v119, 1.0, v119
	v_rcp_f32_e32 v116, v116
	v_rcp_f32_e32 v117, v117
	v_rcp_f32_e32 v118, v118
	v_rcp_f32_e32 v119, v119
	v_mul_f32_e32 v116, v182, v116
	v_mul_f32_e32 v117, v183, v117
	v_mul_f32_e32 v118, v184, v118
	v_mul_f32_e32 v119, v185, v119
	v_mul_f32_e32 v116, v116, v186
	v_mul_f32_e32 v117, v117, v187
	v_mul_f32_e32 v118, v118, v188
	v_mul_f32_e32 v119, v119, v189
	v_cvt_pk_bf16_f32 v102, v116, v117
	v_cvt_pk_bf16_f32 v103, v118, v119
	v_add_u32_e32 v132, 0x42000, v129
	global_store_dwordx4 v132, v[100:103], s[48:49]
	v_fma_f32 v182, v204, v44, v208
	v_fma_f32 v183, v205, v45, v209
	v_fma_f32 v184, v206, v46, v210
	v_fma_f32 v185, v207, v47, v211
	v_fma_f32 v186, v220, v40, v224
	v_fma_f32 v187, v221, v41, v225
	v_fma_f32 v188, v222, v42, v226
	v_fma_f32 v189, v223, v43, v227
	v_fmac_f32_dpp v182, v44, v200 row_shr:1 row_mask:0xf bank_mask:0xf
	v_fmac_f32_dpp v183, v45, v201 row_shr:1 row_mask:0xf bank_mask:0xf
	v_fmac_f32_dpp v184, v46, v202 row_shr:1 row_mask:0xf bank_mask:0xf
	v_fmac_f32_dpp v185, v47, v203 row_shr:1 row_mask:0xf bank_mask:0xf
	v_fmac_f32_dpp v186, v40, v216 row_shr:1 row_mask:0xf bank_mask:0xf
	v_fmac_f32_dpp v187, v41, v217 row_shr:1 row_mask:0xf bank_mask:0xf
	v_fmac_f32_dpp v188, v42, v218 row_shr:1 row_mask:0xf bank_mask:0xf
	v_fmac_f32_dpp v189, v43, v219 row_shr:1 row_mask:0xf bank_mask:0xf
	v_fmac_f32_dpp v182, v44, v196 row_shr:2 row_mask:0xf bank_mask:0xf
	v_fmac_f32_dpp v183, v45, v197 row_shr:2 row_mask:0xf bank_mask:0xf
	v_fmac_f32_dpp v184, v46, v198 row_shr:2 row_mask:0xf bank_mask:0xf
	v_fmac_f32_dpp v185, v47, v199 row_shr:2 row_mask:0xf bank_mask:0xf
	v_fmac_f32_dpp v186, v40, v212 row_shr:2 row_mask:0xf bank_mask:0xf
	v_fmac_f32_dpp v187, v41, v213 row_shr:2 row_mask:0xf bank_mask:0xf
	v_fmac_f32_dpp v188, v42, v214 row_shr:2 row_mask:0xf bank_mask:0xf
	v_fmac_f32_dpp v189, v43, v215 row_shr:2 row_mask:0xf bank_mask:0xf
	v_fmac_f32_dpp v182, v52, v166 row_ror:1 row_mask:0xf bank_mask:0xf
	v_fmac_f32_dpp v183, v53, v167 row_ror:1 row_mask:0xf bank_mask:0xf
	v_fmac_f32_dpp v184, v54, v168 row_ror:1 row_mask:0xf bank_mask:0xf
	v_fmac_f32_dpp v185, v55, v169 row_ror:1 row_mask:0xf bank_mask:0xf
	v_fmac_f32_dpp v186, v48, v174 row_ror:1 row_mask:0xf bank_mask:0xf
	v_fmac_f32_dpp v187, v49, v175 row_ror:1 row_mask:0xf bank_mask:0xf
	v_fmac_f32_dpp v188, v50, v176 row_ror:1 row_mask:0xf bank_mask:0xf
	v_fmac_f32_dpp v189, v51, v177 row_ror:1 row_mask:0xf bank_mask:0xf
	v_fmac_f32_dpp v182, v52, v170 row_ror:2 row_mask:0xf bank_mask:0xf
	v_fmac_f32_dpp v183, v53, v171 row_ror:2 row_mask:0xf bank_mask:0xf
	v_fmac_f32_dpp v184, v54, v172 row_ror:2 row_mask:0xf bank_mask:0xf
	v_fmac_f32_dpp v185, v55, v173 row_ror:2 row_mask:0xf bank_mask:0xf
	v_fmac_f32_dpp v186, v48, v178 row_ror:2 row_mask:0xf bank_mask:0xf
	v_fmac_f32_dpp v187, v49, v179 row_ror:2 row_mask:0xf bank_mask:0xf
	v_fmac_f32_dpp v188, v50, v180 row_ror:2 row_mask:0xf bank_mask:0xf
	v_fmac_f32_dpp v189, v51, v181 row_ror:2 row_mask:0xf bank_mask:0xf
	v_mul_f32_e32 v116, 0xbfb8aa3b, v182
	v_mul_f32_e32 v117, 0xbfb8aa3b, v183
	v_mul_f32_e32 v118, 0xbfb8aa3b, v184
	v_mul_f32_e32 v119, 0xbfb8aa3b, v185
	v_exp_f32_e32 v116, v116
	v_exp_f32_e32 v117, v117
	v_exp_f32_e32 v118, v118
	v_exp_f32_e32 v119, v119
	v_add_f32_e32 v116, 1.0, v116
	v_add_f32_e32 v117, 1.0, v117
	v_add_f32_e32 v118, 1.0, v118
	v_add_f32_e32 v119, 1.0, v119
	v_rcp_f32_e32 v116, v116
	v_rcp_f32_e32 v117, v117
	v_rcp_f32_e32 v118, v118
	v_rcp_f32_e32 v119, v119
	v_mul_f32_e32 v116, v182, v116
	v_mul_f32_e32 v117, v183, v117
	v_mul_f32_e32 v118, v184, v118
	v_mul_f32_e32 v119, v185, v119
	v_mul_f32_e32 v116, v116, v186
	v_mul_f32_e32 v117, v117, v187
	v_mul_f32_e32 v118, v118, v188
	v_mul_f32_e32 v119, v119, v189
	v_cvt_pk_bf16_f32 v114, v116, v117
	v_cvt_pk_bf16_f32 v115, v118, v119
	v_add_u32_e32 v132, 0x2c000, v129
	global_store_dwordx4 v132, v[112:115], s[48:49]
	v_fma_f32 v182, v204, v52, v208
	v_fma_f32 v183, v205, v53, v209
	v_fma_f32 v184, v206, v54, v210
	v_fma_f32 v185, v207, v55, v211
	v_fma_f32 v186, v220, v48, v224
	v_fma_f32 v187, v221, v49, v225
	v_fma_f32 v188, v222, v50, v226
	v_fma_f32 v189, v223, v51, v227
	v_fmac_f32_dpp v182, v52, v200 row_shr:1 row_mask:0xf bank_mask:0xf
	v_fmac_f32_dpp v183, v53, v201 row_shr:1 row_mask:0xf bank_mask:0xf
	v_fmac_f32_dpp v184, v54, v202 row_shr:1 row_mask:0xf bank_mask:0xf
	v_fmac_f32_dpp v185, v55, v203 row_shr:1 row_mask:0xf bank_mask:0xf
	v_fmac_f32_dpp v186, v48, v216 row_shr:1 row_mask:0xf bank_mask:0xf
	v_fmac_f32_dpp v187, v49, v217 row_shr:1 row_mask:0xf bank_mask:0xf
	v_fmac_f32_dpp v188, v50, v218 row_shr:1 row_mask:0xf bank_mask:0xf
	v_fmac_f32_dpp v189, v51, v219 row_shr:1 row_mask:0xf bank_mask:0xf
	v_fmac_f32_dpp v182, v52, v196 row_shr:2 row_mask:0xf bank_mask:0xf
	v_fmac_f32_dpp v183, v53, v197 row_shr:2 row_mask:0xf bank_mask:0xf
	v_fmac_f32_dpp v184, v54, v198 row_shr:2 row_mask:0xf bank_mask:0xf
	v_fmac_f32_dpp v185, v55, v199 row_shr:2 row_mask:0xf bank_mask:0xf
	v_fmac_f32_dpp v186, v48, v212 row_shr:2 row_mask:0xf bank_mask:0xf
	v_fmac_f32_dpp v187, v49, v213 row_shr:2 row_mask:0xf bank_mask:0xf
	v_fmac_f32_dpp v188, v50, v214 row_shr:2 row_mask:0xf bank_mask:0xf
	v_fmac_f32_dpp v189, v51, v215 row_shr:2 row_mask:0xf bank_mask:0xf
	v_fmac_f32_dpp v182, v60, v166 row_ror:1 row_mask:0xf bank_mask:0xf
	v_fmac_f32_dpp v183, v61, v167 row_ror:1 row_mask:0xf bank_mask:0xf
	v_fmac_f32_dpp v184, v62, v168 row_ror:1 row_mask:0xf bank_mask:0xf
	v_fmac_f32_dpp v185, v63, v169 row_ror:1 row_mask:0xf bank_mask:0xf
	v_fmac_f32_dpp v186, v56, v174 row_ror:1 row_mask:0xf bank_mask:0xf
	v_fmac_f32_dpp v187, v57, v175 row_ror:1 row_mask:0xf bank_mask:0xf
	v_fmac_f32_dpp v188, v58, v176 row_ror:1 row_mask:0xf bank_mask:0xf
	v_fmac_f32_dpp v189, v59, v177 row_ror:1 row_mask:0xf bank_mask:0xf
	v_fmac_f32_dpp v182, v60, v170 row_ror:2 row_mask:0xf bank_mask:0xf
	v_fmac_f32_dpp v183, v61, v171 row_ror:2 row_mask:0xf bank_mask:0xf
	v_fmac_f32_dpp v184, v62, v172 row_ror:2 row_mask:0xf bank_mask:0xf
	v_fmac_f32_dpp v185, v63, v173 row_ror:2 row_mask:0xf bank_mask:0xf
	v_fmac_f32_dpp v186, v56, v178 row_ror:2 row_mask:0xf bank_mask:0xf
	v_fmac_f32_dpp v187, v57, v179 row_ror:2 row_mask:0xf bank_mask:0xf
	v_fmac_f32_dpp v188, v58, v180 row_ror:2 row_mask:0xf bank_mask:0xf
	v_fmac_f32_dpp v189, v59, v181 row_ror:2 row_mask:0xf bank_mask:0xf
	v_mul_f32_e32 v116, 0xbfb8aa3b, v182
	v_mul_f32_e32 v117, 0xbfb8aa3b, v183
	v_mul_f32_e32 v118, 0xbfb8aa3b, v184
	v_mul_f32_e32 v119, 0xbfb8aa3b, v185
	v_exp_f32_e32 v116, v116
	v_exp_f32_e32 v117, v117
	v_exp_f32_e32 v118, v118
	v_exp_f32_e32 v119, v119
	v_add_f32_e32 v116, 1.0, v116
	v_add_f32_e32 v117, 1.0, v117
	v_add_f32_e32 v118, 1.0, v118
	v_add_f32_e32 v119, 1.0, v119
	v_rcp_f32_e32 v116, v116
	v_rcp_f32_e32 v117, v117
	v_rcp_f32_e32 v118, v118
	v_rcp_f32_e32 v119, v119
	v_mul_f32_e32 v116, v182, v116
	v_mul_f32_e32 v117, v183, v117
	v_mul_f32_e32 v118, v184, v118
	v_mul_f32_e32 v119, v185, v119
	v_mul_f32_e32 v116, v116, v186
	v_mul_f32_e32 v117, v117, v187
	v_mul_f32_e32 v118, v118, v188
	v_mul_f32_e32 v119, v119, v189
	v_cvt_pk_bf16_f32 v140, v116, v117
	v_cvt_pk_bf16_f32 v141, v118, v119
	v_add_u32_e32 v132, 0x16000, v129
	global_store_dwordx4 v132, v[138:141], s[48:49]
	v_fma_f32 v182, v204, v60, v208
	v_fma_f32 v183, v205, v61, v209
	v_fma_f32 v184, v206, v62, v210
	v_fma_f32 v185, v207, v63, v211
	v_fma_f32 v186, v220, v56, v224
	v_fma_f32 v187, v221, v57, v225
	v_fma_f32 v188, v222, v58, v226
	v_fma_f32 v189, v223, v59, v227
	v_fmac_f32_dpp v182, v60, v200 row_shr:1 row_mask:0xf bank_mask:0xf
	v_fmac_f32_dpp v183, v61, v201 row_shr:1 row_mask:0xf bank_mask:0xf
	v_fmac_f32_dpp v184, v62, v202 row_shr:1 row_mask:0xf bank_mask:0xf
	v_fmac_f32_dpp v185, v63, v203 row_shr:1 row_mask:0xf bank_mask:0xf
	v_fmac_f32_dpp v186, v56, v216 row_shr:1 row_mask:0xf bank_mask:0xf
	v_fmac_f32_dpp v187, v57, v217 row_shr:1 row_mask:0xf bank_mask:0xf
	v_fmac_f32_dpp v188, v58, v218 row_shr:1 row_mask:0xf bank_mask:0xf
	v_fmac_f32_dpp v189, v59, v219 row_shr:1 row_mask:0xf bank_mask:0xf
	v_fmac_f32_dpp v182, v60, v196 row_shr:2 row_mask:0xf bank_mask:0xf
	v_fmac_f32_dpp v183, v61, v197 row_shr:2 row_mask:0xf bank_mask:0xf
	v_fmac_f32_dpp v184, v62, v198 row_shr:2 row_mask:0xf bank_mask:0xf
	v_fmac_f32_dpp v185, v63, v199 row_shr:2 row_mask:0xf bank_mask:0xf
	v_fmac_f32_dpp v186, v56, v212 row_shr:2 row_mask:0xf bank_mask:0xf
	v_fmac_f32_dpp v187, v57, v213 row_shr:2 row_mask:0xf bank_mask:0xf
	v_fmac_f32_dpp v188, v58, v214 row_shr:2 row_mask:0xf bank_mask:0xf
	v_fmac_f32_dpp v189, v59, v215 row_shr:2 row_mask:0xf bank_mask:0xf
	v_mul_f32_e32 v116, 0xbfb8aa3b, v182
	v_mul_f32_e32 v117, 0xbfb8aa3b, v183
	v_mul_f32_e32 v118, 0xbfb8aa3b, v184
	v_mul_f32_e32 v119, 0xbfb8aa3b, v185
	v_exp_f32_e32 v116, v116
	v_exp_f32_e32 v117, v117
	v_exp_f32_e32 v118, v118
	v_exp_f32_e32 v119, v119
	v_add_f32_e32 v116, 1.0, v116
	v_add_f32_e32 v117, 1.0, v117
	v_add_f32_e32 v118, 1.0, v118
	v_add_f32_e32 v119, 1.0, v119
	v_rcp_f32_e32 v116, v116
	v_rcp_f32_e32 v117, v117
	v_rcp_f32_e32 v118, v118
	v_rcp_f32_e32 v119, v119
	v_mul_f32_e32 v116, v182, v116
	v_mul_f32_e32 v117, v183, v117
	v_mul_f32_e32 v118, v184, v118
	v_mul_f32_e32 v119, v185, v119
	v_mul_f32_e32 v116, v116, v186
	v_mul_f32_e32 v117, v117, v187
	v_mul_f32_e32 v118, v118, v188
	v_mul_f32_e32 v119, v119, v189
	v_cvt_pk_bf16_f32 v144, v116, v117
	v_cvt_pk_bf16_f32 v145, v118, v119
	s_mov_b64 exec, s[4:5]
	global_store_dwordx4 v129, v[142:145], s[48:49]
	s_mov_b64 exec, -1
	v_fma_f32 v182, v204, v4, v208
	v_fma_f32 v183, v205, v5, v209
	v_fma_f32 v184, v206, v6, v210
	v_fma_f32 v185, v207, v7, v211
	v_fma_f32 v186, v220, v0, v224
	v_fma_f32 v187, v221, v1, v225
	v_fma_f32 v188, v222, v2, v226
	v_fma_f32 v189, v223, v3, v227
	v_fmac_f32_dpp v182, v4, v200 row_shr:1 row_mask:0xf bank_mask:0xf
	v_fmac_f32_dpp v183, v5, v201 row_shr:1 row_mask:0xf bank_mask:0xf
	v_fmac_f32_dpp v184, v6, v202 row_shr:1 row_mask:0xf bank_mask:0xf
	v_fmac_f32_dpp v185, v7, v203 row_shr:1 row_mask:0xf bank_mask:0xf
	v_fmac_f32_dpp v186, v0, v216 row_shr:1 row_mask:0xf bank_mask:0xf
	v_fmac_f32_dpp v187, v1, v217 row_shr:1 row_mask:0xf bank_mask:0xf
	v_fmac_f32_dpp v188, v2, v218 row_shr:1 row_mask:0xf bank_mask:0xf
	v_fmac_f32_dpp v189, v3, v219 row_shr:1 row_mask:0xf bank_mask:0xf
	v_fmac_f32_dpp v182, v4, v196 row_shr:2 row_mask:0xf bank_mask:0xf
	v_fmac_f32_dpp v183, v5, v197 row_shr:2 row_mask:0xf bank_mask:0xf
	v_fmac_f32_dpp v184, v6, v198 row_shr:2 row_mask:0xf bank_mask:0xf
	v_fmac_f32_dpp v185, v7, v199 row_shr:2 row_mask:0xf bank_mask:0xf
	v_fmac_f32_dpp v186, v0, v212 row_shr:2 row_mask:0xf bank_mask:0xf
	v_fmac_f32_dpp v187, v1, v213 row_shr:2 row_mask:0xf bank_mask:0xf
	v_fmac_f32_dpp v188, v2, v214 row_shr:2 row_mask:0xf bank_mask:0xf
	v_fmac_f32_dpp v189, v3, v215 row_shr:2 row_mask:0xf bank_mask:0xf
	v_fmac_f32_dpp v182, v12, v166 row_ror:1 row_mask:0xf bank_mask:0xf
	v_fmac_f32_dpp v183, v13, v167 row_ror:1 row_mask:0xf bank_mask:0xf
	v_fmac_f32_dpp v184, v14, v168 row_ror:1 row_mask:0xf bank_mask:0xf
	v_fmac_f32_dpp v185, v15, v169 row_ror:1 row_mask:0xf bank_mask:0xf
	v_fmac_f32_dpp v186, v8, v174 row_ror:1 row_mask:0xf bank_mask:0xf
	v_fmac_f32_dpp v187, v9, v175 row_ror:1 row_mask:0xf bank_mask:0xf
	v_fmac_f32_dpp v188, v10, v176 row_ror:1 row_mask:0xf bank_mask:0xf
	v_fmac_f32_dpp v189, v11, v177 row_ror:1 row_mask:0xf bank_mask:0xf
	v_fmac_f32_dpp v182, v12, v170 row_ror:2 row_mask:0xf bank_mask:0xf
	v_fmac_f32_dpp v183, v13, v171 row_ror:2 row_mask:0xf bank_mask:0xf
	v_fmac_f32_dpp v184, v14, v172 row_ror:2 row_mask:0xf bank_mask:0xf
	v_fmac_f32_dpp v185, v15, v173 row_ror:2 row_mask:0xf bank_mask:0xf
	v_fmac_f32_dpp v186, v8, v178 row_ror:2 row_mask:0xf bank_mask:0xf
	v_fmac_f32_dpp v187, v9, v179 row_ror:2 row_mask:0xf bank_mask:0xf
	v_fmac_f32_dpp v188, v10, v180 row_ror:2 row_mask:0xf bank_mask:0xf
	v_fmac_f32_dpp v189, v11, v181 row_ror:2 row_mask:0xf bank_mask:0xf
	v_mul_f32_e32 v116, 0xbfb8aa3b, v182
	v_mul_f32_e32 v117, 0xbfb8aa3b, v183
	v_mul_f32_e32 v118, 0xbfb8aa3b, v184
	v_mul_f32_e32 v119, 0xbfb8aa3b, v185
	v_exp_f32_e32 v116, v116
	v_exp_f32_e32 v117, v117
	v_exp_f32_e32 v118, v118
	v_exp_f32_e32 v119, v119
	v_add_f32_e32 v116, 1.0, v116
	v_add_f32_e32 v117, 1.0, v117
	v_add_f32_e32 v118, 1.0, v118
	v_add_f32_e32 v119, 1.0, v119
	v_rcp_f32_e32 v116, v116
	v_rcp_f32_e32 v117, v117
	v_rcp_f32_e32 v118, v118
	v_rcp_f32_e32 v119, v119
	v_mul_f32_e32 v116, v182, v116
	v_mul_f32_e32 v117, v183, v117
	v_mul_f32_e32 v118, v184, v118
	v_mul_f32_e32 v119, v185, v119
	v_mul_f32_e32 v116, v116, v186
	v_mul_f32_e32 v117, v117, v187
	v_mul_f32_e32 v118, v118, v188
	v_mul_f32_e32 v119, v119, v189
	v_cvt_pk_bf16_f32 v70, v116, v117
	v_cvt_pk_bf16_f32 v71, v118, v119
	v_add_u32_e32 v132, 0xf2000, v129
	global_store_dwordx4 v132, v[68:71], s[48:49]
	v_fma_f32 v182, v204, v12, v208
	v_fma_f32 v183, v205, v13, v209
	v_fma_f32 v184, v206, v14, v210
	v_fma_f32 v185, v207, v15, v211
	v_fma_f32 v186, v220, v8, v224
	v_fma_f32 v187, v221, v9, v225
	v_fma_f32 v188, v222, v10, v226
	v_fma_f32 v189, v223, v11, v227
	v_fmac_f32_dpp v182, v12, v200 row_shr:1 row_mask:0xf bank_mask:0xf
	v_fmac_f32_dpp v183, v13, v201 row_shr:1 row_mask:0xf bank_mask:0xf
	v_fmac_f32_dpp v184, v14, v202 row_shr:1 row_mask:0xf bank_mask:0xf
	v_fmac_f32_dpp v185, v15, v203 row_shr:1 row_mask:0xf bank_mask:0xf
	v_fmac_f32_dpp v186, v8, v216 row_shr:1 row_mask:0xf bank_mask:0xf
	v_fmac_f32_dpp v187, v9, v217 row_shr:1 row_mask:0xf bank_mask:0xf
	v_fmac_f32_dpp v188, v10, v218 row_shr:1 row_mask:0xf bank_mask:0xf
	v_fmac_f32_dpp v189, v11, v219 row_shr:1 row_mask:0xf bank_mask:0xf
	v_fmac_f32_dpp v182, v12, v196 row_shr:2 row_mask:0xf bank_mask:0xf
	v_fmac_f32_dpp v183, v13, v197 row_shr:2 row_mask:0xf bank_mask:0xf
	v_fmac_f32_dpp v184, v14, v198 row_shr:2 row_mask:0xf bank_mask:0xf
	v_fmac_f32_dpp v185, v15, v199 row_shr:2 row_mask:0xf bank_mask:0xf
	v_fmac_f32_dpp v186, v8, v212 row_shr:2 row_mask:0xf bank_mask:0xf
	v_fmac_f32_dpp v187, v9, v213 row_shr:2 row_mask:0xf bank_mask:0xf
	v_fmac_f32_dpp v188, v10, v214 row_shr:2 row_mask:0xf bank_mask:0xf
	v_fmac_f32_dpp v189, v11, v215 row_shr:2 row_mask:0xf bank_mask:0xf
	v_fmac_f32_dpp v182, v20, v166 row_ror:1 row_mask:0xf bank_mask:0xf
	v_fmac_f32_dpp v183, v21, v167 row_ror:1 row_mask:0xf bank_mask:0xf
	v_fmac_f32_dpp v184, v22, v168 row_ror:1 row_mask:0xf bank_mask:0xf
	v_fmac_f32_dpp v185, v23, v169 row_ror:1 row_mask:0xf bank_mask:0xf
	v_fmac_f32_dpp v186, v16, v174 row_ror:1 row_mask:0xf bank_mask:0xf
	v_fmac_f32_dpp v187, v17, v175 row_ror:1 row_mask:0xf bank_mask:0xf
	v_fmac_f32_dpp v188, v18, v176 row_ror:1 row_mask:0xf bank_mask:0xf
	v_fmac_f32_dpp v189, v19, v177 row_ror:1 row_mask:0xf bank_mask:0xf
	v_fmac_f32_dpp v182, v20, v170 row_ror:2 row_mask:0xf bank_mask:0xf
	v_fmac_f32_dpp v183, v21, v171 row_ror:2 row_mask:0xf bank_mask:0xf
	v_fmac_f32_dpp v184, v22, v172 row_ror:2 row_mask:0xf bank_mask:0xf
	v_fmac_f32_dpp v185, v23, v173 row_ror:2 row_mask:0xf bank_mask:0xf
	v_fmac_f32_dpp v186, v16, v178 row_ror:2 row_mask:0xf bank_mask:0xf
	v_fmac_f32_dpp v187, v17, v179 row_ror:2 row_mask:0xf bank_mask:0xf
	v_fmac_f32_dpp v188, v18, v180 row_ror:2 row_mask:0xf bank_mask:0xf
	v_fmac_f32_dpp v189, v19, v181 row_ror:2 row_mask:0xf bank_mask:0xf
	v_mul_f32_e32 v116, 0xbfb8aa3b, v182
	v_mul_f32_e32 v117, 0xbfb8aa3b, v183
	v_mul_f32_e32 v118, 0xbfb8aa3b, v184
	v_mul_f32_e32 v119, 0xbfb8aa3b, v185
	v_exp_f32_e32 v116, v116
	v_exp_f32_e32 v117, v117
	v_exp_f32_e32 v118, v118
	v_exp_f32_e32 v119, v119
	v_add_f32_e32 v116, 1.0, v116
	v_add_f32_e32 v117, 1.0, v117
	v_add_f32_e32 v118, 1.0, v118
	v_add_f32_e32 v119, 1.0, v119
	v_rcp_f32_e32 v116, v116
	v_rcp_f32_e32 v117, v117
	v_rcp_f32_e32 v118, v118
	v_rcp_f32_e32 v119, v119
	v_mul_f32_e32 v116, v182, v116
	v_mul_f32_e32 v117, v183, v117
	v_mul_f32_e32 v118, v184, v118
	v_mul_f32_e32 v119, v185, v119
	v_mul_f32_e32 v116, v116, v186
	v_mul_f32_e32 v117, v117, v187
	v_mul_f32_e32 v118, v118, v188
	v_mul_f32_e32 v119, v119, v189
	v_cvt_pk_bf16_f32 v78, v116, v117
	v_cvt_pk_bf16_f32 v79, v118, v119
	v_add_u32_e32 v132, 0xdc000, v129
	global_store_dwordx4 v132, v[76:79], s[48:49]
	v_fma_f32 v182, v204, v20, v208
	v_fma_f32 v183, v205, v21, v209
	v_fma_f32 v184, v206, v22, v210
	v_fma_f32 v185, v207, v23, v211
	v_fma_f32 v186, v220, v16, v224
	v_fma_f32 v187, v221, v17, v225
	v_fma_f32 v188, v222, v18, v226
	v_fma_f32 v189, v223, v19, v227
	v_fmac_f32_dpp v182, v20, v200 row_shr:1 row_mask:0xf bank_mask:0xf
	v_fmac_f32_dpp v183, v21, v201 row_shr:1 row_mask:0xf bank_mask:0xf
	v_fmac_f32_dpp v184, v22, v202 row_shr:1 row_mask:0xf bank_mask:0xf
	v_fmac_f32_dpp v185, v23, v203 row_shr:1 row_mask:0xf bank_mask:0xf
	v_fmac_f32_dpp v186, v16, v216 row_shr:1 row_mask:0xf bank_mask:0xf
	v_fmac_f32_dpp v187, v17, v217 row_shr:1 row_mask:0xf bank_mask:0xf
	v_fmac_f32_dpp v188, v18, v218 row_shr:1 row_mask:0xf bank_mask:0xf
	v_fmac_f32_dpp v189, v19, v219 row_shr:1 row_mask:0xf bank_mask:0xf
	v_fmac_f32_dpp v182, v20, v196 row_shr:2 row_mask:0xf bank_mask:0xf
	v_fmac_f32_dpp v183, v21, v197 row_shr:2 row_mask:0xf bank_mask:0xf
	v_fmac_f32_dpp v184, v22, v198 row_shr:2 row_mask:0xf bank_mask:0xf
	v_fmac_f32_dpp v185, v23, v199 row_shr:2 row_mask:0xf bank_mask:0xf
	v_fmac_f32_dpp v186, v16, v212 row_shr:2 row_mask:0xf bank_mask:0xf
	v_fmac_f32_dpp v187, v17, v213 row_shr:2 row_mask:0xf bank_mask:0xf
	v_fmac_f32_dpp v188, v18, v214 row_shr:2 row_mask:0xf bank_mask:0xf
	v_fmac_f32_dpp v189, v19, v215 row_shr:2 row_mask:0xf bank_mask:0xf
	v_fmac_f32_dpp v182, v28, v166 row_ror:1 row_mask:0xf bank_mask:0xf
	v_fmac_f32_dpp v183, v29, v167 row_ror:1 row_mask:0xf bank_mask:0xf
	v_fmac_f32_dpp v184, v30, v168 row_ror:1 row_mask:0xf bank_mask:0xf
	v_fmac_f32_dpp v185, v31, v169 row_ror:1 row_mask:0xf bank_mask:0xf
	v_fmac_f32_dpp v186, v24, v174 row_ror:1 row_mask:0xf bank_mask:0xf
	v_fmac_f32_dpp v187, v25, v175 row_ror:1 row_mask:0xf bank_mask:0xf
	v_fmac_f32_dpp v188, v26, v176 row_ror:1 row_mask:0xf bank_mask:0xf
	v_fmac_f32_dpp v189, v27, v177 row_ror:1 row_mask:0xf bank_mask:0xf
	v_fmac_f32_dpp v182, v28, v170 row_ror:2 row_mask:0xf bank_mask:0xf
	v_fmac_f32_dpp v183, v29, v171 row_ror:2 row_mask:0xf bank_mask:0xf
	v_fmac_f32_dpp v184, v30, v172 row_ror:2 row_mask:0xf bank_mask:0xf
	v_fmac_f32_dpp v185, v31, v173 row_ror:2 row_mask:0xf bank_mask:0xf
	v_fmac_f32_dpp v186, v24, v178 row_ror:2 row_mask:0xf bank_mask:0xf
	v_fmac_f32_dpp v187, v25, v179 row_ror:2 row_mask:0xf bank_mask:0xf
	v_fmac_f32_dpp v188, v26, v180 row_ror:2 row_mask:0xf bank_mask:0xf
	v_fmac_f32_dpp v189, v27, v181 row_ror:2 row_mask:0xf bank_mask:0xf
	v_mul_f32_e32 v116, 0xbfb8aa3b, v182
	v_mul_f32_e32 v117, 0xbfb8aa3b, v183
	v_mul_f32_e32 v118, 0xbfb8aa3b, v184
	v_mul_f32_e32 v119, 0xbfb8aa3b, v185
	v_exp_f32_e32 v116, v116
	v_exp_f32_e32 v117, v117
	v_exp_f32_e32 v118, v118
	v_exp_f32_e32 v119, v119
	v_add_f32_e32 v116, 1.0, v116
	v_add_f32_e32 v117, 1.0, v117
	v_add_f32_e32 v118, 1.0, v118
	v_add_f32_e32 v119, 1.0, v119
	v_rcp_f32_e32 v116, v116
	v_rcp_f32_e32 v117, v117
	v_rcp_f32_e32 v118, v118
	v_rcp_f32_e32 v119, v119
	v_mul_f32_e32 v116, v182, v116
	v_mul_f32_e32 v117, v183, v117
	v_mul_f32_e32 v118, v184, v118
	v_mul_f32_e32 v119, v185, v119
	v_mul_f32_e32 v116, v116, v186
	v_mul_f32_e32 v117, v117, v187
	v_mul_f32_e32 v118, v118, v188
	v_mul_f32_e32 v119, v119, v189
	v_cvt_pk_bf16_f32 v86, v116, v117
	v_cvt_pk_bf16_f32 v87, v118, v119
	v_add_u32_e32 v132, 0xc6000, v129
	global_store_dwordx4 v132, v[84:87], s[48:49]
	v_fma_f32 v182, v204, v28, v208
	v_fma_f32 v183, v205, v29, v209
	v_fma_f32 v184, v206, v30, v210
	v_fma_f32 v185, v207, v31, v211
	v_fma_f32 v186, v220, v24, v224
	v_fma_f32 v187, v221, v25, v225
	v_fma_f32 v188, v222, v26, v226
	v_fma_f32 v189, v223, v27, v227
	v_fmac_f32_dpp v182, v28, v200 row_shr:1 row_mask:0xf bank_mask:0xf
	v_fmac_f32_dpp v183, v29, v201 row_shr:1 row_mask:0xf bank_mask:0xf
	v_fmac_f32_dpp v184, v30, v202 row_shr:1 row_mask:0xf bank_mask:0xf
	v_fmac_f32_dpp v185, v31, v203 row_shr:1 row_mask:0xf bank_mask:0xf
	v_fmac_f32_dpp v186, v24, v216 row_shr:1 row_mask:0xf bank_mask:0xf
	v_fmac_f32_dpp v187, v25, v217 row_shr:1 row_mask:0xf bank_mask:0xf
	v_fmac_f32_dpp v188, v26, v218 row_shr:1 row_mask:0xf bank_mask:0xf
	v_fmac_f32_dpp v189, v27, v219 row_shr:1 row_mask:0xf bank_mask:0xf
	v_fmac_f32_dpp v182, v28, v196 row_shr:2 row_mask:0xf bank_mask:0xf
	v_fmac_f32_dpp v183, v29, v197 row_shr:2 row_mask:0xf bank_mask:0xf
	v_fmac_f32_dpp v184, v30, v198 row_shr:2 row_mask:0xf bank_mask:0xf
	v_fmac_f32_dpp v185, v31, v199 row_shr:2 row_mask:0xf bank_mask:0xf
	v_fmac_f32_dpp v186, v24, v212 row_shr:2 row_mask:0xf bank_mask:0xf
	v_fmac_f32_dpp v187, v25, v213 row_shr:2 row_mask:0xf bank_mask:0xf
	v_fmac_f32_dpp v188, v26, v214 row_shr:2 row_mask:0xf bank_mask:0xf
	v_fmac_f32_dpp v189, v27, v215 row_shr:2 row_mask:0xf bank_mask:0xf
	v_mul_f32_e32 v116, 0xbfb8aa3b, v182
	v_mul_f32_e32 v117, 0xbfb8aa3b, v183
	v_mul_f32_e32 v118, 0xbfb8aa3b, v184
	v_mul_f32_e32 v119, 0xbfb8aa3b, v185
	v_exp_f32_e32 v116, v116
	v_exp_f32_e32 v117, v117
	v_exp_f32_e32 v118, v118
	v_exp_f32_e32 v119, v119
	v_add_f32_e32 v116, 1.0, v116
	v_add_f32_e32 v117, 1.0, v117
	v_add_f32_e32 v118, 1.0, v118
	v_add_f32_e32 v119, 1.0, v119
	v_rcp_f32_e32 v116, v116
	v_rcp_f32_e32 v117, v117
	v_rcp_f32_e32 v118, v118
	v_rcp_f32_e32 v119, v119
	v_mul_f32_e32 v116, v182, v116
	v_mul_f32_e32 v117, v183, v117
	v_mul_f32_e32 v118, v184, v118
	v_mul_f32_e32 v119, v185, v119
	v_mul_f32_e32 v116, v116, v186
	v_mul_f32_e32 v117, v117, v187
	v_mul_f32_e32 v118, v118, v188
	v_mul_f32_e32 v119, v119, v189
	v_cvt_pk_bf16_f32 v94, v116, v117
	v_cvt_pk_bf16_f32 v95, v118, v119
	v_add_u32_e32 v132, 0xb0000, v129
	s_mov_b64 exec, s[4:5]
	global_store_dwordx4 v132, v[92:95], s[48:49]
	s_mov_b64 exec, -1
